# S5 item Kt stage as an f32 matrix-core GEMM (v_mfma_f32_16x16x4_f32, f32 operands and accumulate): two taus per wave, B fragment shared, LDS traffic and VALU cut
# speedup vs baseline: 1.0034x; 1.0028x over previous
.Lssa_471:
	global_load_dword v48, v[4:5], off
	global_load_dword v49, v[6:7], off
	v_add_co_u32_e32 v37, vcc, 0x200, v37
	s_xor_b64 s[84:85], vcc, -1
	s_and_b64 s[84:85], exec, s[84:85]
	v_lshl_add_u64 v[6:7], v[6:7], 0, s[80:81]
	v_lshl_add_u64 v[4:5], v[4:5], 0, s[80:81]
	s_or_b64 s[4:5], s[84:85], s[4:5]
	s_waitcnt vmcnt(0)
	ds_write_b64 v8, v[48:49]
	v_add_u32_e32 v8, 0x1000, v8
	s_andn2_b64 exec, exec, s[4:5]
	s_cbranch_execnz .Lssa_471
	s_or_b64 exec, exec, s[4:5]
	v_readfirstlane_b32 s98, v208
	s_lshr_b32 s98, s98, 6
	v_and_b32_e32 v12, 15, v210
	v_lshrrev_b32_e32 v13, 4, v210
	s_load_dwordx2 s[84:85], s[22:23], 0x80
	v_lshl_add_u32 v18, s82, 4, v12
	v_lshlrev_b32_e32 v18, 2, v18
	s_waitcnt lgkmcnt(0)
	global_load_dword v18, v18, s[84:85]
	v_lshrrev_b32_e32 v19, 1, v13
	v_lshl_add_u32 v14, v19, 4, v12
	v_lshlrev_b32_e32 v14, 3, v14
	v_and_b32_e32 v15, 1, v13
	v_lshl_add_u32 v14, v15, 2, v14
	v_cmp_eq_u32_e64 s[84:85], 1, v15
	s_lshl_b32 s4, s98, 10
	v_lshl_add_u32 v16, v19, 3, s4
	v_and_b32_e32 v15, 7, v12
	v_lshlrev_b32_e32 v15, 4, v15
	v_lshl_add_u32 v15, v12, 9, v15
	v_lshl_add_u32 v15, v19, 3, v15
	s_lshl_b32 s4, s98, 11
	v_lshl_add_u32 v17, v13, 8, s4
	v_lshl_add_u32 v17, v12, 2, v17
	v_mov_b32_e32 v20, 0
	v_mov_b32_e32 v21, 0
	v_mov_b32_e32 v22, 0
	v_mov_b32_e32 v23, 0
	v_mov_b32_e32 v24, 0
	v_mov_b32_e32 v25, 0
	v_mov_b32_e32 v26, 0
	v_mov_b32_e32 v27, 0
	s_waitcnt lgkmcnt(0)
	s_barrier
	ds_read_b64 v[30:31], v15 offset:16896
	ds_read_b64 v[32:33], v16 offset:0
	ds_read_b64 v[34:35], v16 offset:512
	ds_read_b32 v28, v14 offset:8704
	v_xor_b32_e32 v19, 0x10, v15
	ds_read_b64 v[52:53], v19 offset:16896
	ds_read_b64 v[54:55], v16 offset:16
	ds_read_b64 v[56:57], v16 offset:528
	ds_read_b32 v29, v14 offset:8960
	s_waitcnt lgkmcnt(4)
	v_pk_mul_f32 v[58:59], v[30:31], v[32:33] op_sel:[1,1] op_sel_hi:[0,1]
	v_pk_fma_f32 v[58:59], v[30:31], v[32:33], v[58:59] op_sel_hi:[1,0,1] neg_lo:[0,0,1]
	v_pk_mul_f32 v[60:61], v[30:31], v[34:35] op_sel:[1,1] op_sel_hi:[0,1]
	v_pk_fma_f32 v[60:61], v[30:31], v[34:35], v[60:61] op_sel_hi:[1,0,1] neg_lo:[0,0,1]
	v_cndmask_b32_e64 v62, v58, -v59, s[84:85]
	v_cndmask_b32_e64 v63, v60, -v61, s[84:85]
	s_nop 1
	v_mfma_f32_16x16x4_f32 v[20:23], v62, v28, v[20:23]
	v_mfma_f32_16x16x4_f32 v[24:27], v63, v28, v[24:27]
	v_xor_b32_e32 v19, 0x20, v15
	ds_read_b64 v[30:31], v19 offset:16896
	ds_read_b64 v[32:33], v16 offset:32
	ds_read_b64 v[34:35], v16 offset:544
	ds_read_b32 v28, v14 offset:9216
	s_waitcnt lgkmcnt(4)
	v_pk_mul_f32 v[58:59], v[52:53], v[54:55] op_sel:[1,1] op_sel_hi:[0,1]
	v_pk_fma_f32 v[58:59], v[52:53], v[54:55], v[58:59] op_sel_hi:[1,0,1] neg_lo:[0,0,1]
	v_pk_mul_f32 v[60:61], v[52:53], v[56:57] op_sel:[1,1] op_sel_hi:[0,1]
	v_pk_fma_f32 v[60:61], v[52:53], v[56:57], v[60:61] op_sel_hi:[1,0,1] neg_lo:[0,0,1]
	v_cndmask_b32_e64 v62, v58, -v59, s[84:85]
	v_cndmask_b32_e64 v63, v60, -v61, s[84:85]
	s_nop 1
	v_mfma_f32_16x16x4_f32 v[20:23], v62, v29, v[20:23]
	v_mfma_f32_16x16x4_f32 v[24:27], v63, v29, v[24:27]
	v_xor_b32_e32 v19, 0x30, v15
	ds_read_b64 v[52:53], v19 offset:16896
	ds_read_b64 v[54:55], v16 offset:48
	ds_read_b64 v[56:57], v16 offset:560
	ds_read_b32 v29, v14 offset:9472
	s_waitcnt lgkmcnt(4)
	v_pk_mul_f32 v[58:59], v[30:31], v[32:33] op_sel:[1,1] op_sel_hi:[0,1]
	v_pk_fma_f32 v[58:59], v[30:31], v[32:33], v[58:59] op_sel_hi:[1,0,1] neg_lo:[0,0,1]
	v_pk_mul_f32 v[60:61], v[30:31], v[34:35] op_sel:[1,1] op_sel_hi:[0,1]
	v_pk_fma_f32 v[60:61], v[30:31], v[34:35], v[60:61] op_sel_hi:[1,0,1] neg_lo:[0,0,1]
	v_cndmask_b32_e64 v62, v58, -v59, s[84:85]
	v_cndmask_b32_e64 v63, v60, -v61, s[84:85]
	s_nop 1
	v_mfma_f32_16x16x4_f32 v[20:23], v62, v28, v[20:23]
	v_mfma_f32_16x16x4_f32 v[24:27], v63, v28, v[24:27]
	v_xor_b32_e32 v19, 0x40, v15
	ds_read_b64 v[30:31], v19 offset:16896
	ds_read_b64 v[32:33], v16 offset:64
	ds_read_b64 v[34:35], v16 offset:576
	ds_read_b32 v28, v14 offset:9728
	s_waitcnt lgkmcnt(4)
	v_pk_mul_f32 v[58:59], v[52:53], v[54:55] op_sel:[1,1] op_sel_hi:[0,1]
	v_pk_fma_f32 v[58:59], v[52:53], v[54:55], v[58:59] op_sel_hi:[1,0,1] neg_lo:[0,0,1]
	v_pk_mul_f32 v[60:61], v[52:53], v[56:57] op_sel:[1,1] op_sel_hi:[0,1]
	v_pk_fma_f32 v[60:61], v[52:53], v[56:57], v[60:61] op_sel_hi:[1,0,1] neg_lo:[0,0,1]
	v_cndmask_b32_e64 v62, v58, -v59, s[84:85]
	v_cndmask_b32_e64 v63, v60, -v61, s[84:85]
	s_nop 1
	v_mfma_f32_16x16x4_f32 v[20:23], v62, v29, v[20:23]
	v_mfma_f32_16x16x4_f32 v[24:27], v63, v29, v[24:27]
	v_xor_b32_e32 v19, 0x50, v15
	ds_read_b64 v[52:53], v19 offset:16896
	ds_read_b64 v[54:55], v16 offset:80
	ds_read_b64 v[56:57], v16 offset:592
	ds_read_b32 v29, v14 offset:9984
	s_waitcnt lgkmcnt(4)
	v_pk_mul_f32 v[58:59], v[30:31], v[32:33] op_sel:[1,1] op_sel_hi:[0,1]
	v_pk_fma_f32 v[58:59], v[30:31], v[32:33], v[58:59] op_sel_hi:[1,0,1] neg_lo:[0,0,1]
	v_pk_mul_f32 v[60:61], v[30:31], v[34:35] op_sel:[1,1] op_sel_hi:[0,1]
	v_pk_fma_f32 v[60:61], v[30:31], v[34:35], v[60:61] op_sel_hi:[1,0,1] neg_lo:[0,0,1]
	v_cndmask_b32_e64 v62, v58, -v59, s[84:85]
	v_cndmask_b32_e64 v63, v60, -v61, s[84:85]
	s_nop 1
	v_mfma_f32_16x16x4_f32 v[20:23], v62, v28, v[20:23]
	v_mfma_f32_16x16x4_f32 v[24:27], v63, v28, v[24:27]
	v_xor_b32_e32 v19, 0x60, v15
	ds_read_b64 v[30:31], v19 offset:16896
	ds_read_b64 v[32:33], v16 offset:96
	ds_read_b64 v[34:35], v16 offset:608
	ds_read_b32 v28, v14 offset:10240
	s_waitcnt lgkmcnt(4)
	v_pk_mul_f32 v[58:59], v[52:53], v[54:55] op_sel:[1,1] op_sel_hi:[0,1]
	v_pk_fma_f32 v[58:59], v[52:53], v[54:55], v[58:59] op_sel_hi:[1,0,1] neg_lo:[0,0,1]
	v_pk_mul_f32 v[60:61], v[52:53], v[56:57] op_sel:[1,1] op_sel_hi:[0,1]
	v_pk_fma_f32 v[60:61], v[52:53], v[56:57], v[60:61] op_sel_hi:[1,0,1] neg_lo:[0,0,1]
	v_cndmask_b32_e64 v62, v58, -v59, s[84:85]
	v_cndmask_b32_e64 v63, v60, -v61, s[84:85]
	s_nop 1
	v_mfma_f32_16x16x4_f32 v[20:23], v62, v29, v[20:23]
	v_mfma_f32_16x16x4_f32 v[24:27], v63, v29, v[24:27]
	v_xor_b32_e32 v19, 0x70, v15
	ds_read_b64 v[52:53], v19 offset:16896
	ds_read_b64 v[54:55], v16 offset:112
	ds_read_b64 v[56:57], v16 offset:624
	ds_read_b32 v29, v14 offset:10496
	s_waitcnt lgkmcnt(4)
	v_pk_mul_f32 v[58:59], v[30:31], v[32:33] op_sel:[1,1] op_sel_hi:[0,1]
	v_pk_fma_f32 v[58:59], v[30:31], v[32:33], v[58:59] op_sel_hi:[1,0,1] neg_lo:[0,0,1]
	v_pk_mul_f32 v[60:61], v[30:31], v[34:35] op_sel:[1,1] op_sel_hi:[0,1]
	v_pk_fma_f32 v[60:61], v[30:31], v[34:35], v[60:61] op_sel_hi:[1,0,1] neg_lo:[0,0,1]
	v_cndmask_b32_e64 v62, v58, -v59, s[84:85]
	v_cndmask_b32_e64 v63, v60, -v61, s[84:85]
	s_nop 1
	v_mfma_f32_16x16x4_f32 v[20:23], v62, v28, v[20:23]
	v_mfma_f32_16x16x4_f32 v[24:27], v63, v28, v[24:27]
	v_xor_b32_e32 v19, 0x80, v15
	ds_read_b64 v[30:31], v19 offset:16896
	ds_read_b64 v[32:33], v16 offset:128
	ds_read_b64 v[34:35], v16 offset:640
	ds_read_b32 v28, v14 offset:10752
	s_waitcnt lgkmcnt(4)
	v_pk_mul_f32 v[58:59], v[52:53], v[54:55] op_sel:[1,1] op_sel_hi:[0,1]
	v_pk_fma_f32 v[58:59], v[52:53], v[54:55], v[58:59] op_sel_hi:[1,0,1] neg_lo:[0,0,1]
	v_pk_mul_f32 v[60:61], v[52:53], v[56:57] op_sel:[1,1] op_sel_hi:[0,1]
	v_pk_fma_f32 v[60:61], v[52:53], v[56:57], v[60:61] op_sel_hi:[1,0,1] neg_lo:[0,0,1]
	v_cndmask_b32_e64 v62, v58, -v59, s[84:85]
	v_cndmask_b32_e64 v63, v60, -v61, s[84:85]
	s_nop 1
	v_mfma_f32_16x16x4_f32 v[20:23], v62, v29, v[20:23]
	v_mfma_f32_16x16x4_f32 v[24:27], v63, v29, v[24:27]
	v_xor_b32_e32 v19, 0x90, v15
	ds_read_b64 v[52:53], v19 offset:16896
	ds_read_b64 v[54:55], v16 offset:144
	ds_read_b64 v[56:57], v16 offset:656
	ds_read_b32 v29, v14 offset:11008
	s_waitcnt lgkmcnt(4)
	v_pk_mul_f32 v[58:59], v[30:31], v[32:33] op_sel:[1,1] op_sel_hi:[0,1]
	v_pk_fma_f32 v[58:59], v[30:31], v[32:33], v[58:59] op_sel_hi:[1,0,1] neg_lo:[0,0,1]
	v_pk_mul_f32 v[60:61], v[30:31], v[34:35] op_sel:[1,1] op_sel_hi:[0,1]
	v_pk_fma_f32 v[60:61], v[30:31], v[34:35], v[60:61] op_sel_hi:[1,0,1] neg_lo:[0,0,1]
	v_cndmask_b32_e64 v62, v58, -v59, s[84:85]
	v_cndmask_b32_e64 v63, v60, -v61, s[84:85]
	s_nop 1
	v_mfma_f32_16x16x4_f32 v[20:23], v62, v28, v[20:23]
	v_mfma_f32_16x16x4_f32 v[24:27], v63, v28, v[24:27]
	v_xor_b32_e32 v19, 0xa0, v15
	ds_read_b64 v[30:31], v19 offset:16896
	ds_read_b64 v[32:33], v16 offset:160
	ds_read_b64 v[34:35], v16 offset:672
	ds_read_b32 v28, v14 offset:11264
	s_waitcnt lgkmcnt(4)
	v_pk_mul_f32 v[58:59], v[52:53], v[54:55] op_sel:[1,1] op_sel_hi:[0,1]
	v_pk_fma_f32 v[58:59], v[52:53], v[54:55], v[58:59] op_sel_hi:[1,0,1] neg_lo:[0,0,1]
	v_pk_mul_f32 v[60:61], v[52:53], v[56:57] op_sel:[1,1] op_sel_hi:[0,1]
	v_pk_fma_f32 v[60:61], v[52:53], v[56:57], v[60:61] op_sel_hi:[1,0,1] neg_lo:[0,0,1]
	v_cndmask_b32_e64 v62, v58, -v59, s[84:85]
	v_cndmask_b32_e64 v63, v60, -v61, s[84:85]
	s_nop 1
	v_mfma_f32_16x16x4_f32 v[20:23], v62, v29, v[20:23]
	v_mfma_f32_16x16x4_f32 v[24:27], v63, v29, v[24:27]
	v_xor_b32_e32 v19, 0xb0, v15
	ds_read_b64 v[52:53], v19 offset:16896
	ds_read_b64 v[54:55], v16 offset:176
	ds_read_b64 v[56:57], v16 offset:688
	ds_read_b32 v29, v14 offset:11520
	s_waitcnt lgkmcnt(4)
	v_pk_mul_f32 v[58:59], v[30:31], v[32:33] op_sel:[1,1] op_sel_hi:[0,1]
	v_pk_fma_f32 v[58:59], v[30:31], v[32:33], v[58:59] op_sel_hi:[1,0,1] neg_lo:[0,0,1]
	v_pk_mul_f32 v[60:61], v[30:31], v[34:35] op_sel:[1,1] op_sel_hi:[0,1]
	v_pk_fma_f32 v[60:61], v[30:31], v[34:35], v[60:61] op_sel_hi:[1,0,1] neg_lo:[0,0,1]
	v_cndmask_b32_e64 v62, v58, -v59, s[84:85]
	v_cndmask_b32_e64 v63, v60, -v61, s[84:85]
	s_nop 1
	v_mfma_f32_16x16x4_f32 v[20:23], v62, v28, v[20:23]
	v_mfma_f32_16x16x4_f32 v[24:27], v63, v28, v[24:27]
	v_xor_b32_e32 v19, 0xc0, v15
	ds_read_b64 v[30:31], v19 offset:16896
	ds_read_b64 v[32:33], v16 offset:192
	ds_read_b64 v[34:35], v16 offset:704
	ds_read_b32 v28, v14 offset:11776
	s_waitcnt lgkmcnt(4)
	v_pk_mul_f32 v[58:59], v[52:53], v[54:55] op_sel:[1,1] op_sel_hi:[0,1]
	v_pk_fma_f32 v[58:59], v[52:53], v[54:55], v[58:59] op_sel_hi:[1,0,1] neg_lo:[0,0,1]
	v_pk_mul_f32 v[60:61], v[52:53], v[56:57] op_sel:[1,1] op_sel_hi:[0,1]
	v_pk_fma_f32 v[60:61], v[52:53], v[56:57], v[60:61] op_sel_hi:[1,0,1] neg_lo:[0,0,1]
	v_cndmask_b32_e64 v62, v58, -v59, s[84:85]
	v_cndmask_b32_e64 v63, v60, -v61, s[84:85]
	s_nop 1
	v_mfma_f32_16x16x4_f32 v[20:23], v62, v29, v[20:23]
	v_mfma_f32_16x16x4_f32 v[24:27], v63, v29, v[24:27]
	v_xor_b32_e32 v19, 0xd0, v15
	ds_read_b64 v[52:53], v19 offset:16896
	ds_read_b64 v[54:55], v16 offset:208
	ds_read_b64 v[56:57], v16 offset:720
	ds_read_b32 v29, v14 offset:12032
	s_waitcnt lgkmcnt(4)
	v_pk_mul_f32 v[58:59], v[30:31], v[32:33] op_sel:[1,1] op_sel_hi:[0,1]
	v_pk_fma_f32 v[58:59], v[30:31], v[32:33], v[58:59] op_sel_hi:[1,0,1] neg_lo:[0,0,1]
	v_pk_mul_f32 v[60:61], v[30:31], v[34:35] op_sel:[1,1] op_sel_hi:[0,1]
	v_pk_fma_f32 v[60:61], v[30:31], v[34:35], v[60:61] op_sel_hi:[1,0,1] neg_lo:[0,0,1]
	v_cndmask_b32_e64 v62, v58, -v59, s[84:85]
	v_cndmask_b32_e64 v63, v60, -v61, s[84:85]
	s_nop 1
	v_mfma_f32_16x16x4_f32 v[20:23], v62, v28, v[20:23]
	v_mfma_f32_16x16x4_f32 v[24:27], v63, v28, v[24:27]
	v_xor_b32_e32 v19, 0xe0, v15
	ds_read_b64 v[30:31], v19 offset:16896
	ds_read_b64 v[32:33], v16 offset:224
	ds_read_b64 v[34:35], v16 offset:736
	ds_read_b32 v28, v14 offset:12288
	s_waitcnt lgkmcnt(4)
	v_pk_mul_f32 v[58:59], v[52:53], v[54:55] op_sel:[1,1] op_sel_hi:[0,1]
	v_pk_fma_f32 v[58:59], v[52:53], v[54:55], v[58:59] op_sel_hi:[1,0,1] neg_lo:[0,0,1]
	v_pk_mul_f32 v[60:61], v[52:53], v[56:57] op_sel:[1,1] op_sel_hi:[0,1]
	v_pk_fma_f32 v[60:61], v[52:53], v[56:57], v[60:61] op_sel_hi:[1,0,1] neg_lo:[0,0,1]
	v_cndmask_b32_e64 v62, v58, -v59, s[84:85]
	v_cndmask_b32_e64 v63, v60, -v61, s[84:85]
	s_nop 1
	v_mfma_f32_16x16x4_f32 v[20:23], v62, v29, v[20:23]
	v_mfma_f32_16x16x4_f32 v[24:27], v63, v29, v[24:27]
	v_xor_b32_e32 v19, 0xf0, v15
	ds_read_b64 v[52:53], v19 offset:16896
	ds_read_b64 v[54:55], v16 offset:240
	ds_read_b64 v[56:57], v16 offset:752
	ds_read_b32 v29, v14 offset:12544
	s_waitcnt lgkmcnt(4)
	v_pk_mul_f32 v[58:59], v[30:31], v[32:33] op_sel:[1,1] op_sel_hi:[0,1]
	v_pk_fma_f32 v[58:59], v[30:31], v[32:33], v[58:59] op_sel_hi:[1,0,1] neg_lo:[0,0,1]
	v_pk_mul_f32 v[60:61], v[30:31], v[34:35] op_sel:[1,1] op_sel_hi:[0,1]
	v_pk_fma_f32 v[60:61], v[30:31], v[34:35], v[60:61] op_sel_hi:[1,0,1] neg_lo:[0,0,1]
	v_cndmask_b32_e64 v62, v58, -v59, s[84:85]
	v_cndmask_b32_e64 v63, v60, -v61, s[84:85]
	s_nop 1
	v_mfma_f32_16x16x4_f32 v[20:23], v62, v28, v[20:23]
	v_mfma_f32_16x16x4_f32 v[24:27], v63, v28, v[24:27]
	v_xor_b32_e32 v19, 0x100, v15
	ds_read_b64 v[30:31], v19 offset:16896
	ds_read_b64 v[32:33], v16 offset:256
	ds_read_b64 v[34:35], v16 offset:768
	ds_read_b32 v28, v14 offset:12800
	s_waitcnt lgkmcnt(4)
	v_pk_mul_f32 v[58:59], v[52:53], v[54:55] op_sel:[1,1] op_sel_hi:[0,1]
	v_pk_fma_f32 v[58:59], v[52:53], v[54:55], v[58:59] op_sel_hi:[1,0,1] neg_lo:[0,0,1]
	v_pk_mul_f32 v[60:61], v[52:53], v[56:57] op_sel:[1,1] op_sel_hi:[0,1]
	v_pk_fma_f32 v[60:61], v[52:53], v[56:57], v[60:61] op_sel_hi:[1,0,1] neg_lo:[0,0,1]
	v_cndmask_b32_e64 v62, v58, -v59, s[84:85]
	v_cndmask_b32_e64 v63, v60, -v61, s[84:85]
	s_nop 1
	v_mfma_f32_16x16x4_f32 v[20:23], v62, v29, v[20:23]
	v_mfma_f32_16x16x4_f32 v[24:27], v63, v29, v[24:27]
	v_xor_b32_e32 v19, 0x110, v15
	ds_read_b64 v[52:53], v19 offset:16896
	ds_read_b64 v[54:55], v16 offset:272
	ds_read_b64 v[56:57], v16 offset:784
	ds_read_b32 v29, v14 offset:13056
	s_waitcnt lgkmcnt(4)
	v_pk_mul_f32 v[58:59], v[30:31], v[32:33] op_sel:[1,1] op_sel_hi:[0,1]
	v_pk_fma_f32 v[58:59], v[30:31], v[32:33], v[58:59] op_sel_hi:[1,0,1] neg_lo:[0,0,1]
	v_pk_mul_f32 v[60:61], v[30:31], v[34:35] op_sel:[1,1] op_sel_hi:[0,1]
	v_pk_fma_f32 v[60:61], v[30:31], v[34:35], v[60:61] op_sel_hi:[1,0,1] neg_lo:[0,0,1]
	v_cndmask_b32_e64 v62, v58, -v59, s[84:85]
	v_cndmask_b32_e64 v63, v60, -v61, s[84:85]
	s_nop 1
	v_mfma_f32_16x16x4_f32 v[20:23], v62, v28, v[20:23]
	v_mfma_f32_16x16x4_f32 v[24:27], v63, v28, v[24:27]
	v_xor_b32_e32 v19, 0x120, v15
	ds_read_b64 v[30:31], v19 offset:16896
	ds_read_b64 v[32:33], v16 offset:288
	ds_read_b64 v[34:35], v16 offset:800
	ds_read_b32 v28, v14 offset:13312
	s_waitcnt lgkmcnt(4)
	v_pk_mul_f32 v[58:59], v[52:53], v[54:55] op_sel:[1,1] op_sel_hi:[0,1]
	v_pk_fma_f32 v[58:59], v[52:53], v[54:55], v[58:59] op_sel_hi:[1,0,1] neg_lo:[0,0,1]
	v_pk_mul_f32 v[60:61], v[52:53], v[56:57] op_sel:[1,1] op_sel_hi:[0,1]
	v_pk_fma_f32 v[60:61], v[52:53], v[56:57], v[60:61] op_sel_hi:[1,0,1] neg_lo:[0,0,1]
	v_cndmask_b32_e64 v62, v58, -v59, s[84:85]
	v_cndmask_b32_e64 v63, v60, -v61, s[84:85]
	s_nop 1
	v_mfma_f32_16x16x4_f32 v[20:23], v62, v29, v[20:23]
	v_mfma_f32_16x16x4_f32 v[24:27], v63, v29, v[24:27]
	v_xor_b32_e32 v19, 0x130, v15
	ds_read_b64 v[52:53], v19 offset:16896
	ds_read_b64 v[54:55], v16 offset:304
	ds_read_b64 v[56:57], v16 offset:816
	ds_read_b32 v29, v14 offset:13568
	s_waitcnt lgkmcnt(4)
	v_pk_mul_f32 v[58:59], v[30:31], v[32:33] op_sel:[1,1] op_sel_hi:[0,1]
	v_pk_fma_f32 v[58:59], v[30:31], v[32:33], v[58:59] op_sel_hi:[1,0,1] neg_lo:[0,0,1]
	v_pk_mul_f32 v[60:61], v[30:31], v[34:35] op_sel:[1,1] op_sel_hi:[0,1]
	v_pk_fma_f32 v[60:61], v[30:31], v[34:35], v[60:61] op_sel_hi:[1,0,1] neg_lo:[0,0,1]
	v_cndmask_b32_e64 v62, v58, -v59, s[84:85]
	v_cndmask_b32_e64 v63, v60, -v61, s[84:85]
	s_nop 1
	v_mfma_f32_16x16x4_f32 v[20:23], v62, v28, v[20:23]
	v_mfma_f32_16x16x4_f32 v[24:27], v63, v28, v[24:27]
	v_xor_b32_e32 v19, 0x140, v15
	ds_read_b64 v[30:31], v19 offset:16896
	ds_read_b64 v[32:33], v16 offset:320
	ds_read_b64 v[34:35], v16 offset:832
	ds_read_b32 v28, v14 offset:13824
	s_waitcnt lgkmcnt(4)
	v_pk_mul_f32 v[58:59], v[52:53], v[54:55] op_sel:[1,1] op_sel_hi:[0,1]
	v_pk_fma_f32 v[58:59], v[52:53], v[54:55], v[58:59] op_sel_hi:[1,0,1] neg_lo:[0,0,1]
	v_pk_mul_f32 v[60:61], v[52:53], v[56:57] op_sel:[1,1] op_sel_hi:[0,1]
	v_pk_fma_f32 v[60:61], v[52:53], v[56:57], v[60:61] op_sel_hi:[1,0,1] neg_lo:[0,0,1]
	v_cndmask_b32_e64 v62, v58, -v59, s[84:85]
	v_cndmask_b32_e64 v63, v60, -v61, s[84:85]
	s_nop 1
	v_mfma_f32_16x16x4_f32 v[20:23], v62, v29, v[20:23]
	v_mfma_f32_16x16x4_f32 v[24:27], v63, v29, v[24:27]
	v_xor_b32_e32 v19, 0x150, v15
	ds_read_b64 v[52:53], v19 offset:16896
	ds_read_b64 v[54:55], v16 offset:336
	ds_read_b64 v[56:57], v16 offset:848
	ds_read_b32 v29, v14 offset:14080
	s_waitcnt lgkmcnt(4)
	v_pk_mul_f32 v[58:59], v[30:31], v[32:33] op_sel:[1,1] op_sel_hi:[0,1]
	v_pk_fma_f32 v[58:59], v[30:31], v[32:33], v[58:59] op_sel_hi:[1,0,1] neg_lo:[0,0,1]
	v_pk_mul_f32 v[60:61], v[30:31], v[34:35] op_sel:[1,1] op_sel_hi:[0,1]
	v_pk_fma_f32 v[60:61], v[30:31], v[34:35], v[60:61] op_sel_hi:[1,0,1] neg_lo:[0,0,1]
	v_cndmask_b32_e64 v62, v58, -v59, s[84:85]
	v_cndmask_b32_e64 v63, v60, -v61, s[84:85]
	s_nop 1
	v_mfma_f32_16x16x4_f32 v[20:23], v62, v28, v[20:23]
	v_mfma_f32_16x16x4_f32 v[24:27], v63, v28, v[24:27]
	v_xor_b32_e32 v19, 0x160, v15
	ds_read_b64 v[30:31], v19 offset:16896
	ds_read_b64 v[32:33], v16 offset:352
	ds_read_b64 v[34:35], v16 offset:864
	ds_read_b32 v28, v14 offset:14336
	s_waitcnt lgkmcnt(4)
	v_pk_mul_f32 v[58:59], v[52:53], v[54:55] op_sel:[1,1] op_sel_hi:[0,1]
	v_pk_fma_f32 v[58:59], v[52:53], v[54:55], v[58:59] op_sel_hi:[1,0,1] neg_lo:[0,0,1]
	v_pk_mul_f32 v[60:61], v[52:53], v[56:57] op_sel:[1,1] op_sel_hi:[0,1]
	v_pk_fma_f32 v[60:61], v[52:53], v[56:57], v[60:61] op_sel_hi:[1,0,1] neg_lo:[0,0,1]
	v_cndmask_b32_e64 v62, v58, -v59, s[84:85]
	v_cndmask_b32_e64 v63, v60, -v61, s[84:85]
	s_nop 1
	v_mfma_f32_16x16x4_f32 v[20:23], v62, v29, v[20:23]
	v_mfma_f32_16x16x4_f32 v[24:27], v63, v29, v[24:27]
	v_xor_b32_e32 v19, 0x170, v15
	ds_read_b64 v[52:53], v19 offset:16896
	ds_read_b64 v[54:55], v16 offset:368
	ds_read_b64 v[56:57], v16 offset:880
	ds_read_b32 v29, v14 offset:14592
	s_waitcnt lgkmcnt(4)
	v_pk_mul_f32 v[58:59], v[30:31], v[32:33] op_sel:[1,1] op_sel_hi:[0,1]
	v_pk_fma_f32 v[58:59], v[30:31], v[32:33], v[58:59] op_sel_hi:[1,0,1] neg_lo:[0,0,1]
	v_pk_mul_f32 v[60:61], v[30:31], v[34:35] op_sel:[1,1] op_sel_hi:[0,1]
	v_pk_fma_f32 v[60:61], v[30:31], v[34:35], v[60:61] op_sel_hi:[1,0,1] neg_lo:[0,0,1]
	v_cndmask_b32_e64 v62, v58, -v59, s[84:85]
	v_cndmask_b32_e64 v63, v60, -v61, s[84:85]
	s_nop 1
	v_mfma_f32_16x16x4_f32 v[20:23], v62, v28, v[20:23]
	v_mfma_f32_16x16x4_f32 v[24:27], v63, v28, v[24:27]
	v_xor_b32_e32 v19, 0x180, v15
	ds_read_b64 v[30:31], v19 offset:16896
	ds_read_b64 v[32:33], v16 offset:384
	ds_read_b64 v[34:35], v16 offset:896
	ds_read_b32 v28, v14 offset:14848
	s_waitcnt lgkmcnt(4)
	v_pk_mul_f32 v[58:59], v[52:53], v[54:55] op_sel:[1,1] op_sel_hi:[0,1]
	v_pk_fma_f32 v[58:59], v[52:53], v[54:55], v[58:59] op_sel_hi:[1,0,1] neg_lo:[0,0,1]
	v_pk_mul_f32 v[60:61], v[52:53], v[56:57] op_sel:[1,1] op_sel_hi:[0,1]
	v_pk_fma_f32 v[60:61], v[52:53], v[56:57], v[60:61] op_sel_hi:[1,0,1] neg_lo:[0,0,1]
	v_cndmask_b32_e64 v62, v58, -v59, s[84:85]
	v_cndmask_b32_e64 v63, v60, -v61, s[84:85]
	s_nop 1
	v_mfma_f32_16x16x4_f32 v[20:23], v62, v29, v[20:23]
	v_mfma_f32_16x16x4_f32 v[24:27], v63, v29, v[24:27]
	v_xor_b32_e32 v19, 0x190, v15
	ds_read_b64 v[52:53], v19 offset:16896
	ds_read_b64 v[54:55], v16 offset:400
	ds_read_b64 v[56:57], v16 offset:912
	ds_read_b32 v29, v14 offset:15104
	s_waitcnt lgkmcnt(4)
	v_pk_mul_f32 v[58:59], v[30:31], v[32:33] op_sel:[1,1] op_sel_hi:[0,1]
	v_pk_fma_f32 v[58:59], v[30:31], v[32:33], v[58:59] op_sel_hi:[1,0,1] neg_lo:[0,0,1]
	v_pk_mul_f32 v[60:61], v[30:31], v[34:35] op_sel:[1,1] op_sel_hi:[0,1]
	v_pk_fma_f32 v[60:61], v[30:31], v[34:35], v[60:61] op_sel_hi:[1,0,1] neg_lo:[0,0,1]
	v_cndmask_b32_e64 v62, v58, -v59, s[84:85]
	v_cndmask_b32_e64 v63, v60, -v61, s[84:85]
	s_nop 1
	v_mfma_f32_16x16x4_f32 v[20:23], v62, v28, v[20:23]
	v_mfma_f32_16x16x4_f32 v[24:27], v63, v28, v[24:27]
	v_xor_b32_e32 v19, 0x1a0, v15
	ds_read_b64 v[30:31], v19 offset:16896
	ds_read_b64 v[32:33], v16 offset:416
	ds_read_b64 v[34:35], v16 offset:928
	ds_read_b32 v28, v14 offset:15360
	s_waitcnt lgkmcnt(4)
	v_pk_mul_f32 v[58:59], v[52:53], v[54:55] op_sel:[1,1] op_sel_hi:[0,1]
	v_pk_fma_f32 v[58:59], v[52:53], v[54:55], v[58:59] op_sel_hi:[1,0,1] neg_lo:[0,0,1]
	v_pk_mul_f32 v[60:61], v[52:53], v[56:57] op_sel:[1,1] op_sel_hi:[0,1]
	v_pk_fma_f32 v[60:61], v[52:53], v[56:57], v[60:61] op_sel_hi:[1,0,1] neg_lo:[0,0,1]
	v_cndmask_b32_e64 v62, v58, -v59, s[84:85]
	v_cndmask_b32_e64 v63, v60, -v61, s[84:85]
	s_nop 1
	v_mfma_f32_16x16x4_f32 v[20:23], v62, v29, v[20:23]
	v_mfma_f32_16x16x4_f32 v[24:27], v63, v29, v[24:27]
	v_xor_b32_e32 v19, 0x1b0, v15
	ds_read_b64 v[52:53], v19 offset:16896
	ds_read_b64 v[54:55], v16 offset:432
	ds_read_b64 v[56:57], v16 offset:944
	ds_read_b32 v29, v14 offset:15616
	s_waitcnt lgkmcnt(4)
	v_pk_mul_f32 v[58:59], v[30:31], v[32:33] op_sel:[1,1] op_sel_hi:[0,1]
	v_pk_fma_f32 v[58:59], v[30:31], v[32:33], v[58:59] op_sel_hi:[1,0,1] neg_lo:[0,0,1]
	v_pk_mul_f32 v[60:61], v[30:31], v[34:35] op_sel:[1,1] op_sel_hi:[0,1]
	v_pk_fma_f32 v[60:61], v[30:31], v[34:35], v[60:61] op_sel_hi:[1,0,1] neg_lo:[0,0,1]
	v_cndmask_b32_e64 v62, v58, -v59, s[84:85]
	v_cndmask_b32_e64 v63, v60, -v61, s[84:85]
	s_nop 1
	v_mfma_f32_16x16x4_f32 v[20:23], v62, v28, v[20:23]
	v_mfma_f32_16x16x4_f32 v[24:27], v63, v28, v[24:27]
	v_xor_b32_e32 v19, 0x1c0, v15
	ds_read_b64 v[30:31], v19 offset:16896
	ds_read_b64 v[32:33], v16 offset:448
	ds_read_b64 v[34:35], v16 offset:960
	ds_read_b32 v28, v14 offset:15872
	s_waitcnt lgkmcnt(4)
	v_pk_mul_f32 v[58:59], v[52:53], v[54:55] op_sel:[1,1] op_sel_hi:[0,1]
	v_pk_fma_f32 v[58:59], v[52:53], v[54:55], v[58:59] op_sel_hi:[1,0,1] neg_lo:[0,0,1]
	v_pk_mul_f32 v[60:61], v[52:53], v[56:57] op_sel:[1,1] op_sel_hi:[0,1]
	v_pk_fma_f32 v[60:61], v[52:53], v[56:57], v[60:61] op_sel_hi:[1,0,1] neg_lo:[0,0,1]
	v_cndmask_b32_e64 v62, v58, -v59, s[84:85]
	v_cndmask_b32_e64 v63, v60, -v61, s[84:85]
	s_nop 1
	v_mfma_f32_16x16x4_f32 v[20:23], v62, v29, v[20:23]
	v_mfma_f32_16x16x4_f32 v[24:27], v63, v29, v[24:27]
	v_xor_b32_e32 v19, 0x1d0, v15
	ds_read_b64 v[52:53], v19 offset:16896
	ds_read_b64 v[54:55], v16 offset:464
	ds_read_b64 v[56:57], v16 offset:976
	ds_read_b32 v29, v14 offset:16128
	s_waitcnt lgkmcnt(4)
	v_pk_mul_f32 v[58:59], v[30:31], v[32:33] op_sel:[1,1] op_sel_hi:[0,1]
	v_pk_fma_f32 v[58:59], v[30:31], v[32:33], v[58:59] op_sel_hi:[1,0,1] neg_lo:[0,0,1]
	v_pk_mul_f32 v[60:61], v[30:31], v[34:35] op_sel:[1,1] op_sel_hi:[0,1]
	v_pk_fma_f32 v[60:61], v[30:31], v[34:35], v[60:61] op_sel_hi:[1,0,1] neg_lo:[0,0,1]
	v_cndmask_b32_e64 v62, v58, -v59, s[84:85]
	v_cndmask_b32_e64 v63, v60, -v61, s[84:85]
	s_nop 1
	v_mfma_f32_16x16x4_f32 v[20:23], v62, v28, v[20:23]
	v_mfma_f32_16x16x4_f32 v[24:27], v63, v28, v[24:27]
	v_xor_b32_e32 v19, 0x1e0, v15
	ds_read_b64 v[30:31], v19 offset:16896
	ds_read_b64 v[32:33], v16 offset:480
	ds_read_b64 v[34:35], v16 offset:992
	ds_read_b32 v28, v14 offset:16384
	s_waitcnt lgkmcnt(4)
	v_pk_mul_f32 v[58:59], v[52:53], v[54:55] op_sel:[1,1] op_sel_hi:[0,1]
	v_pk_fma_f32 v[58:59], v[52:53], v[54:55], v[58:59] op_sel_hi:[1,0,1] neg_lo:[0,0,1]
	v_pk_mul_f32 v[60:61], v[52:53], v[56:57] op_sel:[1,1] op_sel_hi:[0,1]
	v_pk_fma_f32 v[60:61], v[52:53], v[56:57], v[60:61] op_sel_hi:[1,0,1] neg_lo:[0,0,1]
	v_cndmask_b32_e64 v62, v58, -v59, s[84:85]
	v_cndmask_b32_e64 v63, v60, -v61, s[84:85]
	s_nop 1
	v_mfma_f32_16x16x4_f32 v[20:23], v62, v29, v[20:23]
	v_mfma_f32_16x16x4_f32 v[24:27], v63, v29, v[24:27]
	v_xor_b32_e32 v19, 0x1f0, v15
	ds_read_b64 v[52:53], v19 offset:16896
	ds_read_b64 v[54:55], v16 offset:496
	ds_read_b64 v[56:57], v16 offset:1008
	ds_read_b32 v29, v14 offset:16640
	s_waitcnt lgkmcnt(4)
	v_pk_mul_f32 v[58:59], v[30:31], v[32:33] op_sel:[1,1] op_sel_hi:[0,1]
	v_pk_fma_f32 v[58:59], v[30:31], v[32:33], v[58:59] op_sel_hi:[1,0,1] neg_lo:[0,0,1]
	v_pk_mul_f32 v[60:61], v[30:31], v[34:35] op_sel:[1,1] op_sel_hi:[0,1]
	v_pk_fma_f32 v[60:61], v[30:31], v[34:35], v[60:61] op_sel_hi:[1,0,1] neg_lo:[0,0,1]
	v_cndmask_b32_e64 v62, v58, -v59, s[84:85]
	v_cndmask_b32_e64 v63, v60, -v61, s[84:85]
	s_nop 1
	v_mfma_f32_16x16x4_f32 v[20:23], v62, v28, v[20:23]
	v_mfma_f32_16x16x4_f32 v[24:27], v63, v28, v[24:27]
	s_waitcnt lgkmcnt(0)
	v_pk_mul_f32 v[58:59], v[52:53], v[54:55] op_sel:[1,1] op_sel_hi:[0,1]
	v_pk_fma_f32 v[58:59], v[52:53], v[54:55], v[58:59] op_sel_hi:[1,0,1] neg_lo:[0,0,1]
	v_pk_mul_f32 v[60:61], v[52:53], v[56:57] op_sel:[1,1] op_sel_hi:[0,1]
	v_pk_fma_f32 v[60:61], v[52:53], v[56:57], v[60:61] op_sel_hi:[1,0,1] neg_lo:[0,0,1]
	v_cndmask_b32_e64 v62, v58, -v59, s[84:85]
	v_cndmask_b32_e64 v63, v60, -v61, s[84:85]
	s_nop 1
	v_mfma_f32_16x16x4_f32 v[20:23], v62, v29, v[20:23]
	v_mfma_f32_16x16x4_f32 v[24:27], v63, v29, v[24:27]
	s_cmp_eq_u32 s98, 0
	s_cselect_b64 s[4:5], -1, 0
	s_waitcnt vmcnt(0)
	s_nop 10
	v_lshl_add_u32 v19, v13, 2, 0
	v_cmp_eq_u32_e32 vcc, v19, v12
	s_nop 3
	s_and_b64 vcc, vcc, s[4:5]
	s_nop 3
	v_cndmask_b32_e32 v19, 0, v18, vcc
	v_add_f32_e32 v20, v20, v19
	v_lshl_add_u32 v19, v13, 2, 1
	v_cmp_eq_u32_e32 vcc, v19, v12
	s_nop 3
	s_and_b64 vcc, vcc, s[4:5]
	s_nop 3
	v_cndmask_b32_e32 v19, 0, v18, vcc
	v_add_f32_e32 v21, v21, v19
	v_lshl_add_u32 v19, v13, 2, 2
	v_cmp_eq_u32_e32 vcc, v19, v12
	s_nop 3
	s_and_b64 vcc, vcc, s[4:5]
	s_nop 3
	v_cndmask_b32_e32 v19, 0, v18, vcc
	v_add_f32_e32 v22, v22, v19
	v_lshl_add_u32 v19, v13, 2, 3
	v_cmp_eq_u32_e32 vcc, v19, v12
	s_nop 3
	s_and_b64 vcc, vcc, s[4:5]
	s_nop 3
	v_cndmask_b32_e32 v19, 0, v18, vcc
	v_add_f32_e32 v23, v23, v19
	s_lshl_b32 s86, s97, 6
	s_lshl_b32 s87, s82, 8
	s_mov_b32 s91, 0
	ds_write_b32 v17, v20 offset:25088
	ds_write_b32 v17, v21 offset:25152
	ds_write_b32 v17, v22 offset:25216
	ds_write_b32 v17, v23 offset:25280
	ds_write_b32 v17, v24 offset:26112
	ds_write_b32 v17, v25 offset:26176
	ds_write_b32 v17, v26 offset:26240
	ds_write_b32 v17, v27 offset:26304
	s_waitcnt lgkmcnt(0)
	s_barrier
	s_branch .Lssa_493
